# attention steady loop head aligned to 256 bytes (code placement)
# baseline (speedup 1.0000x reference)
.LBB0_308:
	v_lshlrev_b32_e32 v39, 1, v36
	v_and_b32_e32 v39, 32, v39
	v_lshlrev_b32_e32 v40, 4, v36
	v_add3_u32 v38, 0, v39, v38
	v_lshlrev_b32_e32 v39, 8, v250
	v_and_b32_e32 v40, 0xc0, v40
	v_add3_u32 v244, v38, v39, v40
	v_max3_f32 v38, v16, v17, v0
	v_max3_f32 v39, v18, v19, v1
	s_mov_b64 s[2:3], 0x60000
	v_max3_f32 v38, v38, v2, v3
	v_max3_f32 v39, v39, v22, v23
	s_cmp_lg_u32 0, -1
	v_max3_f32 v38, v38, v20, v21
	v_max3_f32 v39, v39, v6, v7
	s_mov_b32 s38, 1
	v_max3_f32 v38, v38, v4, v5
	v_max3_f32 v39, v39, v26, v27
	s_mov_b32 s22, 0
	v_max3_f32 v38, v38, v24, v25
	v_max3_f32 v39, v39, v10, v11
	v_lshlrev_b32_e32 v248, 4, v250
	v_max3_f32 v38, v38, v8, v9
	v_max3_f32 v39, v39, v30, v31
	v_lshl_add_u32 v243, v241, 2, s65
	v_max3_f32 v38, v38, v28, v29
	v_max3_f32 v39, v39, v14, v15
	s_nop 0
	v_max3_f32 v38, v38, v12, v13
	s_nop 0
	v_max_f32_e32 v38, v38, v39
	s_nop 0
	v_mov_b32_e32 v39, v38
	s_nop 1
	v_permlane32_swap_b32_e32 v38, v39
	v_max_f32_e32 v38, v38, v39
	s_nop 0
	v_add_f32_e32 v246, v213, v38
	v_sub_f32_e32 v0, v0, v38
	v_sub_f32_e32 v1, v1, v38
	v_sub_f32_e32 v16, v16, v38
	v_sub_f32_e32 v17, v17, v38
	v_sub_f32_e32 v18, v18, v38
	s_nop 0
	v_xor_b32_e32 v64, 0x80000000, v246
	v_mov_b32_e32 v65, v64
	v_mov_b32_e32 v66, v64
	v_mov_b32_e32 v67, v64
	v_mov_b32_e32 v68, v64
	v_mov_b32_e32 v69, v64
	v_mov_b32_e32 v70, v64
	v_mov_b32_e32 v71, v64
	v_mov_b32_e32 v72, v64
	v_mov_b32_e32 v73, v64
	v_mov_b32_e32 v74, v64
	v_mov_b32_e32 v75, v64
	v_mov_b32_e32 v76, v64
	v_mov_b32_e32 v77, v64
	v_mov_b32_e32 v78, v64
	v_mov_b32_e32 v79, v64
	s_waitcnt vmcnt(0) lgkmcnt(0)
	s_barrier
	v_exp_f32_e32 v80, v0
	v_exp_f32_e32 v81, v1
	v_lshl_add_u64 v[0:1], v[32:33], 0, s[2:3]
	s_mov_b32 s2, m0
	s_mov_b32 m0, s63
	s_nop 0
	global_load_lds_dwordx4 v[0:1], off
	s_mov_b32 m0, s2
	s_mov_b64 s[2:3], 0x20000
	v_lshl_add_u64 v[0:1], v[34:35], 0, s[2:3]
	s_cselect_b32 s2, 0, 0
	s_add_i32 s14, s2, s62
	s_add_i32 s2, s14, 0xa000
	s_mov_b32 s3, m0
	s_mov_b32 m0, s2
	s_nop 0
	global_load_lds_dwordx4 v[0:1], off
	s_mov_b32 m0, s3
	s_mov_b64 s[2:3], 0x20080
	v_lshl_add_u64 v[0:1], v[34:35], 0, s[2:3]
	s_add_i32 s14, s14, 0xc000
	s_mov_b32 s2, m0
	s_mov_b32 m0, s14
	s_nop 0
	global_load_lds_dwordx4 v[0:1], off
	s_mov_b32 m0, s2
	ds_read_b128 v[204:207], v247 offset:8192
	ds_read_b128 v[200:203], v247 offset:8704
	ds_read_b128 v[196:199], v247 offset:10240
	ds_read_b128 v[192:195], v247 offset:10752
	ds_read_b128 v[188:191], v247 offset:12288
	ds_read_b128 v[184:187], v247 offset:12800
	ds_read_b128 v[180:183], v247 offset:14336
	ds_read_b128 v[176:179], v247 offset:14848
	v_sub_f32_e32 v2, v2, v38
	v_sub_f32_e32 v19, v19, v38
	v_sub_f32_e32 v3, v3, v38
	v_sub_f32_e32 v20, v20, v38
	v_sub_f32_e32 v4, v4, v38
	v_sub_f32_e32 v21, v21, v38
	v_sub_f32_e32 v5, v5, v38
	v_sub_f32_e32 v22, v22, v38
	v_sub_f32_e32 v6, v6, v38
	v_sub_f32_e32 v23, v23, v38
	v_sub_f32_e32 v7, v7, v38
	v_sub_f32_e32 v24, v24, v38
	v_sub_f32_e32 v8, v8, v38
	v_sub_f32_e32 v25, v25, v38
	v_sub_f32_e32 v9, v9, v38
	v_sub_f32_e32 v26, v26, v38
	v_sub_f32_e32 v10, v10, v38
	v_sub_f32_e32 v27, v27, v38
	v_sub_f32_e32 v11, v11, v38
	v_sub_f32_e32 v28, v28, v38
	v_sub_f32_e32 v12, v12, v38
	v_sub_f32_e32 v29, v29, v38
	v_sub_f32_e32 v13, v13, v38
	v_sub_f32_e32 v30, v30, v38
	v_sub_f32_e32 v14, v14, v38
	v_sub_f32_e32 v31, v31, v38
	v_sub_f32_e32 v15, v15, v38
	v_exp_f32_e32 v96, v16
	v_exp_f32_e32 v97, v17
	v_exp_f32_e32 v98, v18
	v_exp_f32_e32 v99, v19
	v_exp_f32_e32 v100, v20
	v_exp_f32_e32 v101, v21
	v_exp_f32_e32 v102, v22
	v_exp_f32_e32 v103, v23
	v_exp_f32_e32 v104, v24
	v_exp_f32_e32 v105, v25
	v_exp_f32_e32 v106, v26
	v_exp_f32_e32 v107, v27
	v_exp_f32_e32 v108, v28
	v_exp_f32_e32 v109, v29
	v_exp_f32_e32 v110, v30
	v_exp_f32_e32 v111, v31
	v_exp_f32_e32 v82, v2
	v_exp_f32_e32 v83, v3
	v_exp_f32_e32 v84, v4
	v_exp_f32_e32 v85, v5
	v_exp_f32_e32 v86, v6
	v_exp_f32_e32 v87, v7
	v_exp_f32_e32 v88, v8
	v_exp_f32_e32 v89, v9
	v_exp_f32_e32 v90, v10
	v_exp_f32_e32 v91, v11
	v_exp_f32_e32 v92, v12
	v_exp_f32_e32 v93, v13
	v_exp_f32_e32 v94, v14
	v_exp_f32_e32 v95, v15
	s_waitcnt vmcnt(3) lgkmcnt(0)
	s_barrier
	v_and_b32_e32 v0, 3, v36
	v_lshlrev_b32_e32 v1, 10, v37
	s_cmp_lt_i32 s34, 7
	v_cmp_gt_u32_e64 s[2:3], 32, v239
	v_lshlrev_b32_e32 v216, 4, v0
	v_add_lshl_u32 v214, s56, v1, 1
	s_cbranch_scc1 .LBB0_324
	v_mov_b32_e32 v217, v213
	s_add_i32 s23, s34, -5
	v_lshl_add_u64 v[0:1], s[20:21], 1, v[216:217]
	v_mov_b32_e32 v215, v213
	v_lshl_add_u64 v[0:1], v[0:1], 0, v[214:215]
	s_add_u32 s14, s28, s4
	v_mov_b32_e32 v32, v213
	v_mov_b32_e32 v33, v213
	v_mov_b32_e32 v46, v213
	v_mov_b32_e32 v47, v213
	v_lshl_add_u64 v[218:219], s[94:95], 0, v[0:1]
	s_addc_u32 s15, s54, s5
	v_mov_b32_e32 v34, v213
	v_mov_b32_e32 v35, v213
	v_mov_b32_e32 v36, v213
	v_mov_b32_e32 v37, v213
	v_mov_b32_e32 v38, v213
	v_mov_b32_e32 v39, v213
	v_mov_b32_e32 v40, v213
	v_mov_b32_e32 v41, v213
	v_mov_b32_e32 v42, v213
	v_mov_b32_e32 v43, v213
	v_mov_b32_e32 v44, v213
	v_mov_b32_e32 v45, v213
	v_mov_b64_e32 v[62:63], v[46:47]
	v_mov_b64_e32 v[16:17], v[32:33]
	v_mov_b64_e32 v[0:1], v[32:33]
	v_lshl_add_u64 v[220:221], s[14:15], 0, v[212:213]
	s_add_u32 s14, s14, s30
	s_addc_u32 s15, s15, s31
	s_add_u32 s32, s14, 0x48080000
	s_addc_u32 s70, s15, 0
	s_lshl_b64 s[14:15], s[20:21], 1
	s_add_u32 s14, s14, s94
	s_addc_u32 s15, s15, s95
	s_add_u32 s14, s14, s30
	s_addc_u32 s15, s15, s31
	s_add_u32 s98, s14, 0x4c040000
	s_addc_u32 s99, s15, 0
	v_add_u32_e32 v226, v214, v216
	s_mov_b32 s14, 0
	s_movk_i32 s22, 0x4000
	s_movk_i32 s24, 0x2000
	v_mov_b32_e32 v249, 0
	v_mov_b64_e32 v[60:61], v[44:45]
	v_mov_b64_e32 v[58:59], v[42:43]
	v_mov_b64_e32 v[56:57], v[40:41]
	v_mov_b64_e32 v[54:55], v[38:39]
	v_mov_b64_e32 v[52:53], v[36:37]
	v_mov_b64_e32 v[50:51], v[34:35]
	v_mov_b64_e32 v[48:49], v[32:33]
	v_mov_b64_e32 v[18:19], v[34:35]
	v_mov_b64_e32 v[20:21], v[36:37]
	v_mov_b64_e32 v[22:23], v[38:39]
	v_mov_b64_e32 v[24:25], v[40:41]
	v_mov_b64_e32 v[26:27], v[42:43]
	v_mov_b64_e32 v[28:29], v[44:45]
	v_mov_b64_e32 v[30:31], v[46:47]
	v_mov_b64_e32 v[2:3], v[34:35]
	v_mov_b64_e32 v[4:5], v[36:37]
	v_mov_b64_e32 v[6:7], v[38:39]
	v_mov_b64_e32 v[8:9], v[40:41]
	v_mov_b64_e32 v[10:11], v[42:43]
	v_mov_b64_e32 v[12:13], v[44:45]
	v_mov_b64_e32 v[14:15], v[46:47]
	.p2alignl 8, 3212836864
